# code placement: PEER v-part gather loop shifted by 4 bytes, rest of PEER unchanged
# speedup vs baseline: 1.0072x; 1.0031x over previous
.LBB0_760:
	s_andn2_saveexec_b64 s[10:11], s[10:11]
	v_mul_f32_e32 v121, v120, v120
	v_fmamk_f32 v122, v121, 0xba1345e1, v188
	v_fmaak_f32 v122, v121, v122, 0xbcdac9b8
	v_fmaak_f32 v122, v121, v122, 0x3de703be
	v_fmaak_f32 v122, v121, v122, 0xbec09330
	v_fmaak_f32 v121, v121, v122, 0x3e0375d0
	v_fma_f32 v121, |v120|, v121, |v120|
	s_or_b64 exec, exec, s[10:11]
	v_mul_f32_e32 v122, 0x3d14f209, v150
	v_bfi_b32 v118, s81, v119, v118
	v_mul_f32_e32 v12, v122, v12
	v_add_f32_e32 v118, 1.0, v118
	v_mul_f32_e32 v118, v12, v118
	v_mul_f32_e32 v12, 0x3d14f209, v151
	v_mul_f32_e32 v12, v12, v13
	v_bfi_b32 v13, s81, v121, v120
	v_add_f32_e32 v13, 1.0, v13
	v_mul_f32_e32 v119, v12, v13
	v_and_b32_e32 v13, 64, v191
	v_add_u32_e32 v13, 64, v13
	v_xor_b32_e32 v120, 32, v191
	v_cmp_lt_i32_e32 vcc, v120, v13
	v_max_f32_e64 v12, |v118|, |v119|
	v_mov_b32_e32 v123, v16
	v_cndmask_b32_e32 v120, v191, v120, vcc
	v_lshlrev_b32_e32 v226, 2, v120
	ds_bpermute_b32 v120, v226, v12
	v_mov_b32_e32 v124, v16
	s_mov_b32 s10, 0x1010101
	v_mov_b32_e32 v130, 0
	v_lshlrev_b32_e32 v232, 2, v17
	s_waitcnt lgkmcnt(0)
	v_max_f32_e32 v120, v120, v120
	v_max_f32_e32 v12, v12, v120
	v_xor_b32_e32 v120, 16, v191
	v_cmp_lt_i32_e32 vcc, v120, v13
	v_and_b32_e32 v233, 24, v232
	v_mov_b32_e32 v131, v130
	v_cndmask_b32_e32 v120, v191, v120, vcc
	v_lshlrev_b32_e32 v227, 2, v120
	ds_bpermute_b32 v120, v227, v12
	v_mov_b32_e32 v132, v130
	v_mov_b32_e32 v133, v130
	v_mov_b32_e32 v150, v130
	v_mov_b32_e32 v151, v130
	s_waitcnt lgkmcnt(0)
	v_max_f32_e32 v120, v120, v120
	v_max_f32_e32 v12, v12, v120
	v_xor_b32_e32 v120, 8, v191
	v_cmp_lt_i32_e32 vcc, v120, v13
	v_mov_b32_e32 v152, v130
	v_mov_b32_e32 v142, v130
	v_cndmask_b32_e32 v120, v191, v120, vcc
	v_lshlrev_b32_e32 v228, 2, v120
	ds_bpermute_b32 v120, v228, v12
	v_mov_b32_e32 v143, v130
	v_mov_b32_e32 v144, v130
	v_mov_b32_e32 v145, v130
	v_mov_b32_e32 v138, v130
	s_waitcnt lgkmcnt(0)
	v_max_f32_e32 v120, v120, v120
	v_max_f32_e32 v12, v12, v120
	v_xor_b32_e32 v120, 4, v191
	v_cmp_lt_i32_e32 vcc, v120, v13
	v_mov_b32_e32 v139, v130
	v_mov_b32_e32 v140, v130
	v_cndmask_b32_e32 v120, v191, v120, vcc
	v_lshlrev_b32_e32 v229, 2, v120
	ds_bpermute_b32 v120, v229, v12
	v_mov_b32_e32 v141, v130
	v_mov_b32_e32 v134, v130
	v_mov_b32_e32 v135, v130
	v_mov_b32_e32 v136, v130
	s_waitcnt lgkmcnt(0)
	v_max_f32_e32 v120, v120, v120
	v_max_f32_e32 v12, v12, v120
	v_xor_b32_e32 v120, 2, v191
	v_cmp_lt_i32_e32 vcc, v120, v13
	v_mov_b32_e32 v137, v130
	v_mov_b32_e32 v126, v130
	v_cndmask_b32_e32 v120, v191, v120, vcc
	v_lshlrev_b32_e32 v230, 2, v120
	ds_bpermute_b32 v120, v230, v12
	v_mov_b32_e32 v127, v130
	v_mov_b32_e32 v128, v130
	v_mov_b32_e32 v129, v130
	v_mov_b32_e32 v125, v130
	s_waitcnt lgkmcnt(0)
	v_max_f32_e32 v120, v120, v120
	v_max_f32_e32 v12, v12, v120
	v_xor_b32_e32 v120, 1, v191
	v_cmp_lt_i32_e32 vcc, v120, v13
	s_nop 1
	v_cndmask_b32_e32 v13, v191, v120, vcc
	v_lshlrev_b32_e32 v231, 2, v13
	ds_bpermute_b32 v13, v231, v12
	v_cmp_gt_u32_e32 vcc, 8, v158
	s_waitcnt lgkmcnt(0)
	v_max_f32_e32 v13, v13, v13
	v_max_f32_e32 v12, v12, v13
	v_bfe_u32 v12, v12, 23, 8
	v_max_u32_e32 v120, 28, v12
	v_lshlrev_b32_e32 v12, 23, v120
	v_xor_b32_e32 v121, 0x7f800000, v12
	v_mul_f32_e32 v12, v118, v121
	v_mov_b32_e32 v13, v16
	v_cvt_scalef32_pk_fp4_f32 v13, v12, 0, 1.0
	v_and_b32_e32 v122, 0xff, v13
	v_cvt_scalef32_pk_fp4_f32 v123, 0, v12, 1.0
	v_cvt_scalef32_pk_f32_fp4 v[12:13], v122, 1.0
	v_fma_f32 v12, v118, v121, -v12
	v_mul_f32_e32 v12, 4.0, v12
	v_mov_b32_e32 v13, v16
	v_cvt_scalef32_pk_fp4_f32 v13, v12, 0, 1.0
	v_mov_b32_e32 v118, v16
	v_cvt_scalef32_pk_fp4_f32 v118, 0, v12, 1.0
	v_lshlrev_b32_e32 v12, 8, v13
	v_and_or_b32 v122, v12, s74, v122
	v_lshlrev_b32_e32 v12, 8, v118
	v_perm_b32 v118, v12, v123, s75
	v_mul_f32_e32 v12, v119, v121
	v_mov_b32_e32 v13, v16
	v_cvt_scalef32_pk_fp4_f32 v13, v12, 0, 1.0
	v_and_b32_e32 v123, 0xff, v13
	v_cvt_scalef32_pk_fp4_f32 v124, 0, v12, 1.0
	v_cvt_scalef32_pk_f32_fp4 v[12:13], v123, 1.0
	v_fma_f32 v12, v119, v121, -v12
	v_mul_f32_e32 v12, 4.0, v12
	v_mov_b32_e32 v13, v16
	v_cvt_scalef32_pk_fp4_f32 v13, v12, 0, 1.0
	v_mov_b32_e32 v119, v16
	v_cvt_scalef32_pk_fp4_f32 v119, 0, v12, 1.0
	v_lshlrev_b32_e32 v12, 8, v13
	v_and_or_b32 v12, v12, s74, v123
	ds_write2st64_b32 v14, v122, v12 offset0:18 offset1:19
	v_lshlrev_b32_e32 v12, 8, v119
	v_perm_b32 v12, v12, v124, s75
	ds_write2st64_b32 v14, v118, v12 offset0:20 offset1:21
	v_mul_lo_u32 v12, v120, s10
	v_add_u32_e32 v234, 0xfefefeff, v12
	v_add_u32_e32 v235, 0xfcfcfcfd, v12
	v_and_b32_e32 v12, 1, v17
	v_lshlrev_b32_e32 v12, 9, v12
	v_add3_u32 v236, v12, v153, v221
	s_mov_b32 s10, -8
	v_mov_b32_e32 v12, v15
	v_mov_b32_e32 v153, v130
	v_mov_b32_e32 v122, v130
	v_mov_b32_e32 v123, v130
	v_mov_b32_e32 v124, v130
	v_mov_b32_e32 v118, v130
	v_mov_b32_e32 v119, v130
	v_mov_b32_e32 v120, v130
	v_mov_b32_e32 v121, v130
	s_branch .LBB0_764
	s_nop 0

.LBB0_776:
	s_add_i32 s11, s10, 22
	s_and_b32 s11, s11, 30
	s_waitcnt lgkmcnt(0)
	v_lshl_add_u32 v12, s11, 2, v225
	ds_read_b32 v12, v12 offset:32768
	v_lshlrev_b32_sdwa v13, v233, v168 dst_sel:DWORD dst_unused:UNUSED_PAD src0_sel:DWORD src1_sel:BYTE_0
	v_cndmask_b32_e32 v14, 0, v13, vcc
	v_cndmask_b32_e64 v15, v13, 0, vcc
	v_mov_b32_e32 v17, v16
	v_mov_b32_e32 v170, v16
	v_mov_b32_e32 v171, v16
	v_mov_b32_e32 v172, v14
	v_mov_b32_e32 v173, v15
	s_waitcnt vmcnt(7)
	v_mfma_scale_f32_16x16x128_f8f6f4 v[118:121], v[102:105], v[14:17], v[118:121], v187, v234 op_sel_hi:[0,0,0] cbsz:4 blgp:4
	v_lshlrev_b32_sdwa v13, v233, v168 dst_sel:DWORD dst_unused:UNUSED_PAD src0_sel:DWORD src1_sel:BYTE_1
	v_mfma_scale_f32_16x16x128_f8f6f4 v[122:125], v[102:105], v[170:173], v[122:125], v187, v234 op_sel_hi:[0,0,0] cbsz:4 blgp:4
	s_waitcnt vmcnt(6)
	v_mfma_scale_f32_16x16x128_f8f6f4 v[126:129], v[106:109], v[14:17], v[126:129], v187, v234 op_sel_hi:[0,0,0] cbsz:4 blgp:4
	v_mfma_scale_f32_16x16x128_f8f6f4 v[130:133], v[106:109], v[170:173], v[130:133], v187, v234 op_sel_hi:[0,0,0] cbsz:4 blgp:4
	s_waitcnt vmcnt(5)
	v_mfma_scale_f32_16x16x128_f8f6f4 v[134:137], v[110:113], v[14:17], v[134:137], v187, v234 op_sel_hi:[0,0,0] cbsz:4 blgp:4
	v_mfma_scale_f32_16x16x128_f8f6f4 v[138:141], v[110:113], v[170:173], v[138:141], v187, v234 op_sel_hi:[0,0,0] cbsz:4 blgp:4
	s_waitcnt vmcnt(4)
	v_mfma_scale_f32_16x16x128_f8f6f4 v[142:145], v[114:117], v[14:17], v[142:145], v187, v234 op_sel_hi:[0,0,0] cbsz:4 blgp:4
	v_cndmask_b32_e32 v14, 0, v13, vcc
	v_cndmask_b32_e64 v15, v13, 0, vcc
	v_mfma_scale_f32_16x16x128_f8f6f4 v[150:153], v[114:117], v[170:173], v[150:153], v187, v234 op_sel_hi:[0,0,0] cbsz:4 blgp:4
	v_mov_b32_e32 v172, v14
	v_mov_b32_e32 v173, v15
	v_mfma_scale_f32_16x16x128_f8f6f4 v[118:121], v[102:105], v[14:17], v[118:121], v187, v235 op_sel_hi:[0,0,0] cbsz:4 blgp:4
	s_nop 0
	v_mfma_scale_f32_16x16x128_f8f6f4 v[122:125], v[102:105], v[170:173], v[122:125], v187, v235 op_sel_hi:[0,0,0] cbsz:4 blgp:4
	v_mfma_scale_f32_16x16x128_f8f6f4 v[126:129], v[106:109], v[14:17], v[126:129], v187, v235 op_sel_hi:[0,0,0] cbsz:4 blgp:4
	v_mfma_scale_f32_16x16x128_f8f6f4 v[130:133], v[106:109], v[170:173], v[130:133], v187, v235 op_sel_hi:[0,0,0] cbsz:4 blgp:4
	v_mfma_scale_f32_16x16x128_f8f6f4 v[134:137], v[110:113], v[14:17], v[134:137], v187, v235 op_sel_hi:[0,0,0] cbsz:4 blgp:4
	v_mfma_scale_f32_16x16x128_f8f6f4 v[138:141], v[110:113], v[170:173], v[138:141], v187, v235 op_sel_hi:[0,0,0] cbsz:4 blgp:4
	v_mfma_scale_f32_16x16x128_f8f6f4 v[142:145], v[114:117], v[14:17], v[142:145], v187, v235 op_sel_hi:[0,0,0] cbsz:4 blgp:4
	v_mfma_scale_f32_16x16x128_f8f6f4 v[150:153], v[114:117], v[170:173], v[150:153], v187, v235 op_sel_hi:[0,0,0] cbsz:4 blgp:4
	s_add_i32 s11, s10, 15
	s_cmp_gt_u32 s11, 24
	s_cbranch_scc1 .LBB0_763
	s_waitcnt lgkmcnt(0)
	v_ashrrev_i32_e32 v13, 31, v12
	v_lshlrev_b64 v[12:13], 10, v[12:13]
	v_lshl_add_u64 v[12:13], v[182:183], 0, v[12:13]
	global_load_dwordx4 v[102:105], v[12:13], off
	global_load_dwordx4 v[106:109], v[12:13], off offset:256
	global_load_dwordx4 v[110:113], v[12:13], off offset:512
	global_load_dwordx4 v[114:117], v[12:13], off offset:768
	s_branch .LBB0_763
	s_nop 0
